# loop-edge edits in the diff-attention key loop: K-fragment LDS reads lead each step (next-tile global prefetch moved behind them) and the next-tile LDS write moved from after PV to the start of the so
# speedup vs baseline: 1.0063x; 1.0011x over previous
; #define LAS __attribute__((address_space(3)))
; #define MFMA32(a, b, c) __builtin_amdgcn_mfma_f32_32x32x16_bf16((a), (b), (c), 0, 0, 0)
; template <bool DIFF, int NDV>
; __device__ __forceinline__ void attn_tile(f32x16 (&o)[NDV], float& l, const bf16x8 (&qf)[4], const float sref, LAS const char* kc, LAS const char* vc,
;                                           bool masked, int kb0, int qrow) {
;     ...
; #pragma unroll
;     for (int ks = 0; ks < 4; ++ks) { kf[2 * ks] = *(LAS const bf16x8*)(kc + ks * 32); kf[2 * ks + 1] = *(LAS const bf16x8*)(kc + 32 * ATT_KP + ks * 32); }
;     f32x16 s0, s1;
; #pragma unroll
;     for (int i = 0; i < 16; ++i) { s0[i] = 0.f; s1[i] = 0.f; }
; #pragma unroll
;     for (int ks = 0; ks < 4; ++ks) { s0 = MFMA32(kf[2 * ks], qf[ks], s0); s1 = MFMA32(kf[2 * ks + 1], qf[ks], s1); }
;     __builtin_amdgcn_sched_barrier(0);
;     bf16x8 vf[8];
; #pragma unroll
;     for (int d = 0; d < 2; ++d)
; #pragma unroll
;         for (int kk = 0; kk < 4; ++kk) vf[d * 4 + kk] = vtr8(vc + kk * 16 * ATT_VP + d * 64, 8 * ATT_VP);
;     __builtin_amdgcn_sched_barrier(0);
;     if (DIFF && masked) {
; #pragma unroll
;         for (int i = 0; i < 16; ++i) { const int key = kb0 + (i & 3) + 8 * (i >> 2); if (key > qrow) s0[i] = -1e30f; if (key + 32 > qrow) s1[i] = -1e30f; }
.LBB0_43:
	s_cmp_gt_u32 s37, s42
	s_cbranch_scc1 .Lah_skip0
	ds_read_b128 v[80:83], v233
	ds_read_b128 v[148:151], v233 offset:32
	ds_read_b128 v[84:87], v233 offset:8704
	ds_read_b128 v[152:155], v233 offset:8736
	ds_read_b128 v[156:159], v233 offset:64
	ds_read_b128 v[164:167], v233 offset:96
	ds_read_b128 v[160:163], v233 offset:8768
	ds_read_b128 v[234:237], v233 offset:8800
	global_load_dwordx4 v[6:9], v[206:207], off offset:16
	global_load_dwordx4 v[144:147], v[206:207], off
	global_load_dwordx4 v[2:5], v[206:207], off offset:1552
	global_load_dwordx4 v[10:13], v[206:207], off offset:1536
	s_add_i32 s10, s37, 3
	s_min_i32 s10, s10, s40
	s_mul_i32 s76, s10, 0x50000
	v_lshl_add_u64 v[14:15], v[204:205], 0, s[76:77]
	s_sub_i32 s10, s38, 64
	s_cmp_le_u32 s10, s41
	s_waitcnt lgkmcnt(7)
	v_mfma_f32_32x32x16_bf16 v[96:111], v[80:83], v[112:115], 0
	s_waitcnt lgkmcnt(5)
	v_mfma_f32_32x32x16_bf16 v[80:95], v[84:87], v[112:115], 0
	v_mfma_f32_32x32x16_bf16 v[96:111], v[148:151], v[116:119], v[96:111]
	s_waitcnt lgkmcnt(4)
	v_mfma_f32_32x32x16_bf16 v[80:95], v[152:155], v[116:119], v[80:95]
	s_waitcnt lgkmcnt(3)
	v_mfma_f32_32x32x16_bf16 v[96:111], v[156:159], v[120:123], v[96:111]
	s_waitcnt lgkmcnt(1)
	v_mfma_f32_32x32x16_bf16 v[80:95], v[160:163], v[120:123], v[80:95]
	ds_read_b64_tr_b16 v[148:149], v226 offset:34816
	ds_read_b64_tr_b16 v[150:151], v226 offset:37376
	ds_read_b64_tr_b16 v[158:159], v226 offset:37440
	ds_read_b64_tr_b16 v[156:157], v226 offset:34880
	ds_read_b64_tr_b16 v[152:153], v226 offset:39936
	ds_read_b64_tr_b16 v[154:155], v226 offset:42496
	ds_read_b64_tr_b16 v[162:163], v226 offset:42560
	ds_read_b64_tr_b16 v[160:161], v226 offset:40000
	v_mfma_f32_32x32x16_bf16 v[96:111], v[164:167], v[124:127], v[96:111]
	ds_read_b64_tr_b16 v[164:165], v226 offset:45056
	ds_read_b64_tr_b16 v[166:167], v226 offset:47616
	ds_read_b64_tr_b16 v[174:175], v226 offset:47680
	ds_read_b64_tr_b16 v[172:173], v226 offset:45120
	ds_read_b64_tr_b16 v[168:169], v226 offset:50176
	ds_read_b64_tr_b16 v[170:171], v226 offset:52736
	ds_read_b64_tr_b16 v[178:179], v226 offset:52800
	ds_read_b64_tr_b16 v[176:177], v226 offset:50240
	s_waitcnt lgkmcnt(14)
	v_mfma_f32_32x32x16_bf16 v[80:95], v[234:237], v[124:127], v[80:95]
	s_cbranch_scc1 .LBB0_46
	v_add_u32_e32 v0, s38, v198
	v_add_u32_e32 v199, 0xffffff81, v0
	v_cmp_lt_u32_e32 vcc, v199, v231
	s_nop 1
	v_cndmask_b32_e32 v97, v216, v97, vcc
	v_cmp_le_u32_e32 vcc, v199, v231
	s_nop 1
	v_cndmask_b32_e32 v96, v216, v96, vcc
	v_cmp_lt_i32_e32 vcc, v199, v232
	s_nop 1
	v_cndmask_b32_e32 v81, v216, v81, vcc
	v_cmp_le_i32_e32 vcc, v199, v232
	v_add_u32_e32 v199, 0xffffff83, v0
	s_nop 0
	v_cndmask_b32_e32 v80, v216, v80, vcc
	v_cmp_le_u32_e32 vcc, v199, v231
	s_nop 1
	v_cndmask_b32_e32 v98, v216, v98, vcc
	v_cmp_le_i32_e32 vcc, v199, v232
	v_add_u32_e32 v199, 0xffffff84, v0
	s_nop 0
	v_cndmask_b32_e32 v82, v216, v82, vcc
	v_cmp_le_u32_e32 vcc, v199, v231
	s_nop 1
	v_cndmask_b32_e32 v99, v216, v99, vcc
	v_cmp_le_i32_e32 vcc, v199, v232
	v_add_u32_e32 v199, 0xffffff89, v0
	s_nop 0
	v_cndmask_b32_e32 v83, v216, v83, vcc
	v_cmp_le_u32_e32 vcc, v199, v231
	s_nop 1
	v_cndmask_b32_e32 v100, v216, v100, vcc
	v_cmp_le_i32_e32 vcc, v199, v232
	v_add_u32_e32 v199, 0xffffff8a, v0
	s_nop 0
	v_cndmask_b32_e32 v84, v216, v84, vcc
	v_cmp_le_u32_e32 vcc, v199, v231
	s_nop 1
	v_cndmask_b32_e32 v101, v216, v101, vcc
	v_cmp_le_i32_e32 vcc, v199, v232
	v_add_u32_e32 v199, 0xffffff8b, v0
	s_nop 0
	v_cndmask_b32_e32 v85, v216, v85, vcc
	v_cmp_le_u32_e32 vcc, v199, v231
	s_nop 1
	v_cndmask_b32_e32 v102, v216, v102, vcc
	v_cmp_le_i32_e32 vcc, v199, v232
	v_add_u32_e32 v199, 0xffffff8c, v0
	s_nop 0
	v_cndmask_b32_e32 v86, v216, v86, vcc
	v_cmp_le_u32_e32 vcc, v199, v231
	s_nop 1
	v_cndmask_b32_e32 v103, v216, v103, vcc
	v_cmp_le_i32_e32 vcc, v199, v232
	v_add_u32_e32 v199, 0xffffff91, v0
	s_nop 0
	v_cndmask_b32_e32 v87, v216, v87, vcc
	v_cmp_le_u32_e32 vcc, v199, v231
	s_nop 1
	v_cndmask_b32_e32 v104, v216, v104, vcc
	v_cmp_le_i32_e32 vcc, v199, v232
	v_add_u32_e32 v199, 0xffffff92, v0
	s_nop 0
	v_cndmask_b32_e32 v88, v216, v88, vcc
	v_cmp_le_u32_e32 vcc, v199, v231
	s_nop 1
	v_cndmask_b32_e32 v105, v216, v105, vcc
	v_cmp_le_i32_e32 vcc, v199, v232
	v_add_u32_e32 v199, 0xffffff93, v0
	s_nop 0
	v_cndmask_b32_e32 v89, v216, v89, vcc
	v_cmp_le_u32_e32 vcc, v199, v231
	s_nop 1
	v_cndmask_b32_e32 v106, v216, v106, vcc
	v_cmp_le_i32_e32 vcc, v199, v232
	v_add_u32_e32 v199, 0xffffff94, v0
	s_nop 0
	v_cndmask_b32_e32 v90, v216, v90, vcc
	v_cmp_le_u32_e32 vcc, v199, v231
	s_nop 1
	v_cndmask_b32_e32 v107, v216, v107, vcc
	v_cmp_le_i32_e32 vcc, v199, v232
	v_add_u32_e32 v199, 0xffffff99, v0
	s_nop 0
	v_cndmask_b32_e32 v91, v216, v91, vcc
	v_cmp_le_u32_e32 vcc, v199, v231
	s_nop 1
	v_cndmask_b32_e32 v108, v216, v108, vcc
	v_cmp_le_i32_e32 vcc, v199, v232
	v_add_u32_e32 v199, 0xffffff9a, v0
	s_nop 0
	v_cndmask_b32_e32 v92, v216, v92, vcc
	v_cmp_le_u32_e32 vcc, v199, v231
	s_nop 1
	v_cndmask_b32_e32 v109, v216, v109, vcc
	v_cmp_le_i32_e32 vcc, v199, v232
	v_add_u32_e32 v199, 0xffffff9b, v0
	v_add_u32_e32 v0, 0xffffff9c, v0
	v_cndmask_b32_e32 v93, v216, v93, vcc
	v_cmp_le_u32_e32 vcc, v199, v231
	s_nop 1
	v_cndmask_b32_e32 v110, v216, v110, vcc
	v_cmp_le_i32_e32 vcc, v199, v232
	s_nop 1
	v_cndmask_b32_e32 v94, v216, v94, vcc
	v_cmp_le_u32_e32 vcc, v0, v231
	s_nop 1
	v_cndmask_b32_e32 v111, v216, v111, vcc
	v_cmp_le_i32_e32 vcc, v0, v232
	s_nop 1
	v_cndmask_b32_e32 v95, v216, v95, vcc

; __device__ __forceinline__ float fast_exp2(float x) { return __builtin_amdgcn_exp2f(x); }
; #define MFMA32(a, b, c) __builtin_amdgcn_mfma_f32_32x32x16_bf16((a), (b), (c), 0, 0, 0)
; template <bool DIFF, int NDV>
; __device__ __forceinline__ void attn_tile(f32x16 (&o)[NDV], float& l, const bf16x8 (&qf)[4], const float sref, LAS const char* kc, LAS const char* vc,
;                                           bool masked, int kb0, int qrow) {
;     ...
;     if (sref != 0.f) {
; #pragma unroll
;         for (int i = 0; i < 16; ++i) { s0[i] -= sref; s1[i] -= sref; }
;     }
;     float rs = 0.f;
; #pragma unroll
;     for (int i = 0; i < 16; ++i) { s0[i] = fast_exp2(s0[i]); s1[i] = fast_exp2(s1[i]); rs += s0[i] + s1[i]; }
;     l += rs;
;     bf16x8 pb[4];
;     pb[0] = pack8(s0, 0); pb[1] = pack8(s0, 1); pb[2] = pack8(s1, 0); pb[3] = pack8(s1, 1);
;     if (NDV == 4) {
;         bf16x8 vf2[8];
; #pragma unroll
;         for (int d = 0; d < 2; ++d)
; #pragma unroll
;             for (int kk = 0; kk < 4; ++kk) vf2[d * 4 + kk] = vtr8(vc + kk * 16 * ATT_VP + (d + 2) * 64, 8 * ATT_VP);
;         __builtin_amdgcn_sched_barrier(0);
; #pragma unroll
;         for (int kk = 0; kk < 4; ++kk) { o[0] = MFMA32(vf[kk], pb[kk], o[0]); o[1] = MFMA32(vf[4 + kk], pb[kk], o[1]); }
; #pragma unroll
;         for (int kk = 0; kk < 4; ++kk) { o[2] = MFMA32(vf2[kk], pb[kk], o[2]); o[NDV - 1] = MFMA32(vf2[4 + kk], pb[kk], o[NDV - 1]); }
.LBB0_48:
	s_waitcnt vmcnt(6)
	ds_write_b128 v230, v[128:131] offset:17408
	s_waitcnt vmcnt(5)
	ds_write_b128 v230, v[136:139] offset:17424
	s_waitcnt vmcnt(4)
	ds_write_b128 v228, v[132:135] offset:55296
	s_waitcnt vmcnt(4)
	ds_write_b128 v228, v[140:143] offset:55312
	v_exp_f32_e32 v199, v96
	s_nop 7
	v_exp_f32_e32 v236, v80
	v_exp_f32_e32 v0, v97
	v_exp_f32_e32 v206, v81
	v_exp_f32_e32 v237, v82
	v_add_f32_e32 v207, v236, v199
	v_exp_f32_e32 v234, v83
	v_pk_add_f32 v[80:81], v[206:207], v[0:1]
	v_exp_f32_e32 v207, v98
	v_pk_add_f32 v[96:97], v[80:81], v[80:81] op_sel_hi:[0,1]
	v_exp_f32_e32 v96, v99
	v_exp_f32_e32 v98, v85
	v_add_f32_e32 v235, v237, v207
	v_pk_add_f32 v[80:81], v[234:235], v[96:97]
	s_nop 0
	v_pk_add_f32 v[82:83], v[80:81], v[80:81] op_sel_hi:[0,1]
	v_exp_f32_e32 v97, v100
	v_exp_f32_e32 v235, v84
	v_exp_f32_e32 v82, v101
	v_exp_f32_e32 v100, v87
	v_add_f32_e32 v99, v235, v97
	v_pk_add_f32 v[80:81], v[98:99], v[82:83]
	v_exp_f32_e32 v83, v102
	v_pk_add_f32 v[84:85], v[80:81], v[80:81] op_sel_hi:[0,1]
	v_exp_f32_e32 v99, v86
	v_exp_f32_e32 v84, v103
	v_exp_f32_e32 v102, v89
	v_cvt_pk_bf16_f32 v82, v97, v82
	v_add_f32_e32 v101, v99, v83
	v_pk_add_f32 v[80:81], v[100:101], v[84:85]
	v_exp_f32_e32 v85, v104
	v_pk_add_f32 v[86:87], v[80:81], v[80:81] op_sel_hi:[0,1]
	v_exp_f32_e32 v101, v88
	v_exp_f32_e32 v86, v105
	v_exp_f32_e32 v104, v91
	v_cvt_pk_bf16_f32 v83, v83, v84
	v_add_f32_e32 v103, v101, v85
	v_pk_add_f32 v[80:81], v[102:103], v[86:87]
	v_exp_f32_e32 v87, v106
	v_pk_add_f32 v[88:89], v[80:81], v[80:81] op_sel_hi:[0,1]
	v_exp_f32_e32 v103, v90
	v_exp_f32_e32 v88, v107
	v_exp_f32_e32 v106, v93
	v_cvt_pk_bf16_f32 v84, v85, v86
	v_add_f32_e32 v105, v103, v87
	v_pk_add_f32 v[80:81], v[104:105], v[88:89]
	v_exp_f32_e32 v89, v108
	v_pk_add_f32 v[90:91], v[80:81], v[80:81] op_sel_hi:[0,1]
	v_exp_f32_e32 v105, v92
	v_exp_f32_e32 v90, v109
	v_exp_f32_e32 v108, v95
	v_cvt_pk_bf16_f32 v85, v87, v88
	v_add_f32_e32 v107, v105, v89
	v_pk_add_f32 v[80:81], v[106:107], v[90:91]
	v_exp_f32_e32 v91, v110
	v_pk_add_f32 v[92:93], v[80:81], v[80:81] op_sel_hi:[0,1]
	v_exp_f32_e32 v107, v94
	v_exp_f32_e32 v92, v111
	v_cvt_pk_bf16_f32 v86, v89, v90
	v_cvt_pk_bf16_f32 v88, v236, v206
	v_add_f32_e32 v109, v107, v91
	v_pk_add_f32 v[80:81], v[108:109], v[92:93]
	v_cvt_pk_bf16_f32 v87, v91, v92
	v_add_f32_e32 v80, v80, v81
	v_cvt_pk_bf16_f32 v81, v207, v96
	v_cvt_pk_bf16_f32 v89, v237, v234
	v_cvt_pk_bf16_f32 v90, v235, v98
	v_cvt_pk_bf16_f32 v91, v99, v100
	v_cvt_pk_bf16_f32 v92, v101, v102
	v_cvt_pk_bf16_f32 v93, v103, v104
	v_cvt_pk_bf16_f32 v94, v105, v106
	v_cvt_pk_bf16_f32 v95, v107, v108
	ds_read_b64_tr_b16 v[96:97], v226 offset:34944
	ds_read_b64_tr_b16 v[98:99], v226 offset:37504
	ds_read_b64_tr_b16 v[100:101], v226 offset:40064
	ds_read_b64_tr_b16 v[102:103], v226 offset:42624
	ds_read_b64_tr_b16 v[104:105], v226 offset:45184
	ds_read_b64_tr_b16 v[106:107], v226 offset:47744
	ds_read_b64_tr_b16 v[108:109], v226 offset:50304
	ds_read_b64_tr_b16 v[110:111], v226 offset:52864
	ds_read_b64_tr_b16 v[234:235], v226 offset:35008
	ds_read_b64_tr_b16 v[236:237], v226 offset:37568
	ds_read_b64_tr_b16 v[238:239], v226 offset:40128
	ds_read_b64_tr_b16 v[240:241], v226 offset:42688
	ds_read_b64_tr_b16 v[242:243], v226 offset:45248
	ds_read_b64_tr_b16 v[244:245], v226 offset:47808
	ds_read_b64_tr_b16 v[246:247], v226 offset:50368
	ds_read_b64_tr_b16 v[248:249], v226 offset:52928
	v_add_f32_e32 v203, v203, v80
	v_cvt_pk_bf16_f32 v80, v199, v0
	s_nop 1
	v_mfma_f32_32x32x16_bf16 v[64:79], v[148:151], v[80:83], v[64:79]
	s_waitcnt lgkmcnt(14)
	v_mfma_f32_32x32x16_bf16 v[48:63], v[156:159], v[80:83], v[48:63]
	v_mfma_f32_32x32x16_bf16 v[32:47], v[96:99], v[80:83], v[32:47]
	s_waitcnt lgkmcnt(6)
	v_mfma_f32_32x32x16_bf16 v[16:31], v[234:237], v[80:83], v[16:31]
	v_mfma_f32_32x32x16_bf16 v[64:79], v[152:155], v[84:87], v[64:79]
	v_mfma_f32_32x32x16_bf16 v[48:63], v[160:163], v[84:87], v[48:63]
	v_mfma_f32_32x32x16_bf16 v[32:47], v[100:103], v[84:87], v[32:47]
	s_waitcnt lgkmcnt(4)
	v_mfma_f32_32x32x16_bf16 v[16:31], v[238:241], v[84:87], v[16:31]
	v_mfma_f32_32x32x16_bf16 v[64:79], v[164:167], v[88:91], v[64:79]
	v_mfma_f32_32x32x16_bf16 v[48:63], v[172:175], v[88:91], v[48:63]
	v_mfma_f32_32x32x16_bf16 v[32:47], v[104:107], v[88:91], v[32:47]
	s_waitcnt lgkmcnt(2)
	v_mfma_f32_32x32x16_bf16 v[16:31], v[242:245], v[88:91], v[16:31]
	v_mfma_f32_32x32x16_bf16 v[64:79], v[168:171], v[92:95], v[64:79]
	v_mfma_f32_32x32x16_bf16 v[48:63], v[176:179], v[92:95], v[48:63]
	v_mfma_f32_32x32x16_bf16 v[32:47], v[108:111], v[92:95], v[32:47]
	s_waitcnt lgkmcnt(0)
	v_mfma_f32_32x32x16_bf16 v[16:31], v[246:249], v[92:95], v[16:31]
	s_branch .Law_w0done

; #define LAS __attribute__((address_space(3)))
; #define MFMA32(a, b, c) __builtin_amdgcn_mfma_f32_32x32x16_bf16((a), (b), (c), 0, 0, 0)
; template <bool DIFF, int NDV>
; __device__ __forceinline__ void attn_tile(f32x16 (&o)[NDV], float& l, const bf16x8 (&qf)[4], const float sref, LAS const char* kc, LAS const char* vc,
;                                           bool masked, int kb0, int qrow) {
;     ...
; #pragma unroll
;     for (int ks = 0; ks < 4; ++ks) { kf[2 * ks] = *(LAS const bf16x8*)(kc + ks * 32); kf[2 * ks + 1] = *(LAS const bf16x8*)(kc + 32 * ATT_KP + ks * 32); }
;     f32x16 s0, s1;
; #pragma unroll
;     for (int i = 0; i < 16; ++i) { s0[i] = 0.f; s1[i] = 0.f; }
; #pragma unroll
;     for (int ks = 0; ks < 4; ++ks) { s0 = MFMA32(kf[2 * ks], qf[ks], s0); s1 = MFMA32(kf[2 * ks + 1], qf[ks], s1); }
;     __builtin_amdgcn_sched_barrier(0);
;     bf16x8 vf[8];
; #pragma unroll
;     for (int d = 0; d < 2; ++d)
; #pragma unroll
;         for (int kk = 0; kk < 4; ++kk) vf[d * 4 + kk] = vtr8(vc + kk * 16 * ATT_VP + d * 64, 8 * ATT_VP);
;     __builtin_amdgcn_sched_barrier(0);
;     if (DIFF && masked) {
; #pragma unroll
;         for (int i = 0; i < 16; ++i) { const int key = kb0 + (i & 3) + 8 * (i >> 2); if (key > qrow) s0[i] = -1e30f; if (key + 32 > qrow) s1[i] = -1e30f; }
.Law_w0done:
	s_waitcnt lgkmcnt(0)
	s_barrier
	s_cmp_ge_u32 s37, s42
	s_cbranch_scc1 .Lah_skip1
	ds_read_b128 v[80:83], v233 offset:17408
	ds_read_b128 v[148:151], v233 offset:17440
	ds_read_b128 v[84:87], v233 offset:26112
	ds_read_b128 v[152:155], v233 offset:26144
	ds_read_b128 v[156:159], v233 offset:17472
	ds_read_b128 v[172:175], v233 offset:17504
	ds_read_b128 v[160:163], v233 offset:26176
	ds_read_b128 v[234:237], v233 offset:26208
	global_load_dwordx4 v[136:139], v[14:15], off offset:16
	global_load_dwordx4 v[128:131], v[14:15], off
	global_load_dwordx4 v[140:143], v[14:15], off offset:1552
	global_load_dwordx4 v[132:135], v[14:15], off offset:1536
	s_add_i32 s10, s37, 4
	s_min_i32 s10, s10, s40
	s_mul_i32 s76, s10, 0x50000
	v_lshl_add_u64 v[206:207], v[204:205], 0, s[76:77]
	s_cmp_le_u32 s38, s41
	s_waitcnt lgkmcnt(7)
	v_mfma_f32_32x32x16_bf16 v[96:111], v[80:83], v[112:115], 0
	s_waitcnt lgkmcnt(5)
	v_mfma_f32_32x32x16_bf16 v[80:95], v[84:87], v[112:115], 0
	v_mfma_f32_32x32x16_bf16 v[96:111], v[148:151], v[116:119], v[96:111]
	s_waitcnt lgkmcnt(4)
	v_mfma_f32_32x32x16_bf16 v[80:95], v[152:155], v[116:119], v[80:95]
	s_waitcnt lgkmcnt(3)
	v_mfma_f32_32x32x16_bf16 v[96:111], v[156:159], v[120:123], v[96:111]
	s_waitcnt lgkmcnt(1)
	v_mfma_f32_32x32x16_bf16 v[80:95], v[160:163], v[120:123], v[80:95]
	ds_read_b64_tr_b16 v[152:153], v226 offset:55296
	ds_read_b64_tr_b16 v[154:155], v226 offset:57856
	ds_read_b64_tr_b16 v[166:167], v226 offset:57920
	ds_read_b64_tr_b16 v[164:165], v226 offset:55360
	ds_read_b64_tr_b16 v[160:161], v226 offset:60416
	ds_read_b64_tr_b16 v[162:163], v226 offset:62976
	ds_read_b64_tr_b16 v[170:171], v226 offset:63040
	ds_read_b64_tr_b16 v[168:169], v226 offset:60480
	v_mfma_f32_32x32x16_bf16 v[96:111], v[172:175], v[124:127], v[96:111]
	ds_read_b64_tr_b16 v[174:175], v227 offset:33280
	ds_read_b64_tr_b16 v[156:157], v227 offset:35840
	ds_read_b64_tr_b16 v[148:149], v227 offset:35904
	ds_read_b64_tr_b16 v[178:179], v227 offset:33344
	ds_read_b64_tr_b16 v[172:173], v227 offset:30720
	ds_read_b64_tr_b16 v[158:159], v227 offset:38400
	ds_read_b64_tr_b16 v[176:177], v227 offset:30784
	ds_read_b64_tr_b16 v[150:151], v227 offset:38464
	s_waitcnt lgkmcnt(14)
	v_mfma_f32_32x32x16_bf16 v[80:95], v[234:237], v[124:127], v[80:95]
	s_cbranch_scc1 .LBB0_52
	v_add_u32_e32 v0, s38, v198
	v_subrev_u32_e32 v14, 63, v0
	v_cmp_lt_u32_e32 vcc, v14, v231
	s_nop 1
	v_cndmask_b32_e32 v97, v216, v97, vcc
	v_cmp_le_u32_e32 vcc, v14, v231
	s_nop 1
	v_cndmask_b32_e32 v96, v216, v96, vcc
	v_cmp_lt_i32_e32 vcc, v14, v232
	s_nop 1
	v_cndmask_b32_e32 v81, v216, v81, vcc
	v_cmp_le_i32_e32 vcc, v14, v232
	v_subrev_u32_e32 v14, 61, v0
	s_nop 0
	v_cndmask_b32_e32 v80, v216, v80, vcc
	v_cmp_le_u32_e32 vcc, v14, v231
	s_nop 1
	v_cndmask_b32_e32 v98, v216, v98, vcc
	v_cmp_le_i32_e32 vcc, v14, v232
	v_subrev_u32_e32 v14, 60, v0
	s_nop 0
	v_cndmask_b32_e32 v82, v216, v82, vcc
	v_cmp_le_u32_e32 vcc, v14, v231
	s_nop 1
	v_cndmask_b32_e32 v99, v216, v99, vcc
	v_cmp_le_i32_e32 vcc, v14, v232
	v_subrev_u32_e32 v14, 55, v0
	s_nop 0
	v_cndmask_b32_e32 v83, v216, v83, vcc
	v_cmp_le_u32_e32 vcc, v14, v231
	s_nop 1
	v_cndmask_b32_e32 v100, v216, v100, vcc
	v_cmp_le_i32_e32 vcc, v14, v232
	v_subrev_u32_e32 v14, 54, v0
	s_nop 0
	v_cndmask_b32_e32 v84, v216, v84, vcc
	v_cmp_le_u32_e32 vcc, v14, v231
	s_nop 1
	v_cndmask_b32_e32 v101, v216, v101, vcc
	v_cmp_le_i32_e32 vcc, v14, v232
	v_subrev_u32_e32 v14, 53, v0
	s_nop 0
	v_cndmask_b32_e32 v85, v216, v85, vcc
	v_cmp_le_u32_e32 vcc, v14, v231
	s_nop 1
	v_cndmask_b32_e32 v102, v216, v102, vcc
	v_cmp_le_i32_e32 vcc, v14, v232
	v_subrev_u32_e32 v14, 52, v0
	s_nop 0
	v_cndmask_b32_e32 v86, v216, v86, vcc
	v_cmp_le_u32_e32 vcc, v14, v231
	s_nop 1
	v_cndmask_b32_e32 v103, v216, v103, vcc
	v_cmp_le_i32_e32 vcc, v14, v232
	v_subrev_u32_e32 v14, 47, v0
	s_nop 0
	v_cndmask_b32_e32 v87, v216, v87, vcc
	v_cmp_le_u32_e32 vcc, v14, v231
	s_nop 1
	v_cndmask_b32_e32 v104, v216, v104, vcc
	v_cmp_le_i32_e32 vcc, v14, v232
	v_subrev_u32_e32 v14, 46, v0
	s_nop 0
	v_cndmask_b32_e32 v88, v216, v88, vcc
	v_cmp_le_u32_e32 vcc, v14, v231
	s_nop 1
	v_cndmask_b32_e32 v105, v216, v105, vcc
	v_cmp_le_i32_e32 vcc, v14, v232
	v_subrev_u32_e32 v14, 45, v0
	s_nop 0
	v_cndmask_b32_e32 v89, v216, v89, vcc
	v_cmp_le_u32_e32 vcc, v14, v231
	s_nop 1
	v_cndmask_b32_e32 v106, v216, v106, vcc
	v_cmp_le_i32_e32 vcc, v14, v232
	v_subrev_u32_e32 v14, 44, v0
	s_nop 0
	v_cndmask_b32_e32 v90, v216, v90, vcc
	v_cmp_le_u32_e32 vcc, v14, v231
	s_nop 1
	v_cndmask_b32_e32 v107, v216, v107, vcc
	v_cmp_le_i32_e32 vcc, v14, v232
	v_subrev_u32_e32 v14, 39, v0
	s_nop 0
	v_cndmask_b32_e32 v91, v216, v91, vcc
	v_cmp_le_u32_e32 vcc, v14, v231
	s_nop 1
	v_cndmask_b32_e32 v108, v216, v108, vcc
	v_cmp_le_i32_e32 vcc, v14, v232
	v_subrev_u32_e32 v14, 38, v0
	s_nop 0
	v_cndmask_b32_e32 v92, v216, v92, vcc
	v_cmp_le_u32_e32 vcc, v14, v231
	s_nop 1
	v_cndmask_b32_e32 v109, v216, v109, vcc
	v_cmp_le_i32_e32 vcc, v14, v232
	v_subrev_u32_e32 v14, 37, v0
	v_subrev_u32_e32 v0, 36, v0
	v_cndmask_b32_e32 v93, v216, v93, vcc
	v_cmp_le_u32_e32 vcc, v14, v231
	s_nop 1
	v_cndmask_b32_e32 v110, v216, v110, vcc
	v_cmp_le_i32_e32 vcc, v14, v232
	s_nop 1
	v_cndmask_b32_e32 v94, v216, v94, vcc
	v_cmp_le_u32_e32 vcc, v0, v231
	s_nop 1
	v_cndmask_b32_e32 v111, v216, v111, vcc
	v_cmp_le_i32_e32 vcc, v0, v232
	s_nop 1
	v_cndmask_b32_e32 v95, v216, v95, vcc

; __device__ __forceinline__ float fast_exp2(float x) { return __builtin_amdgcn_exp2f(x); }
; #define MFMA32(a, b, c) __builtin_amdgcn_mfma_f32_32x32x16_bf16((a), (b), (c), 0, 0, 0)
; template <bool DIFF, int NDV>
; __device__ __forceinline__ void attn_tile(f32x16 (&o)[NDV], float& l, const bf16x8 (&qf)[4], const float sref, LAS const char* kc, LAS const char* vc,
;                                           bool masked, int kb0, int qrow) {
;     ...
;     if (sref != 0.f) {
; #pragma unroll
;         for (int i = 0; i < 16; ++i) { s0[i] -= sref; s1[i] -= sref; }
;     }
;     float rs = 0.f;
; #pragma unroll
;     for (int i = 0; i < 16; ++i) { s0[i] = fast_exp2(s0[i]); s1[i] = fast_exp2(s1[i]); rs += s0[i] + s1[i]; }
;     l += rs;
;     bf16x8 pb[4];
;     pb[0] = pack8(s0, 0); pb[1] = pack8(s0, 1); pb[2] = pack8(s1, 0); pb[3] = pack8(s1, 1);
;     if (NDV == 4) {
;         bf16x8 vf2[8];
; #pragma unroll
;         for (int d = 0; d < 2; ++d)
; #pragma unroll
;             for (int kk = 0; kk < 4; ++kk) vf2[d * 4 + kk] = vtr8(vc + kk * 16 * ATT_VP + (d + 2) * 64, 8 * ATT_VP);
;         __builtin_amdgcn_sched_barrier(0);
; #pragma unroll
;         for (int kk = 0; kk < 4; ++kk) { o[0] = MFMA32(vf[kk], pb[kk], o[0]); o[1] = MFMA32(vf[4 + kk], pb[kk], o[1]); }
; #pragma unroll
;         for (int kk = 0; kk < 4; ++kk) { o[2] = MFMA32(vf2[kk], pb[kk], o[2]); o[NDV - 1] = MFMA32(vf2[4 + kk], pb[kk], o[NDV - 1]); }
.LBB0_54:
	s_cmp_ge_u32 s37, s39
	s_cbranch_scc1 .Law_nw1
	s_waitcnt vmcnt(6)
	ds_write_b128 v230, v[144:147]
	ds_write_b128 v230, v[6:9] offset:16
	s_waitcnt vmcnt(4)
	ds_write_b128 v228, v[10:13] offset:34816
	ds_write_b128 v228, v[2:5] offset:34832
.Law_nw1:
	v_exp_f32_e32 v199, v96
	s_nop 7
	v_exp_f32_e32 v236, v80
	v_exp_f32_e32 v0, v97
	v_exp_f32_e32 v14, v81
	v_exp_f32_e32 v237, v82
	v_add_f32_e32 v15, v236, v199
	v_exp_f32_e32 v234, v83
	v_pk_add_f32 v[80:81], v[14:15], v[0:1]
	v_exp_f32_e32 v15, v98
	v_pk_add_f32 v[96:97], v[80:81], v[80:81] op_sel_hi:[0,1]
	v_exp_f32_e32 v96, v99
	v_exp_f32_e32 v98, v85
	v_add_f32_e32 v235, v237, v15
	v_pk_add_f32 v[80:81], v[234:235], v[96:97]
	s_nop 0
	v_pk_add_f32 v[82:83], v[80:81], v[80:81] op_sel_hi:[0,1]
	v_exp_f32_e32 v97, v100
	v_exp_f32_e32 v235, v84
	v_exp_f32_e32 v82, v101
	v_exp_f32_e32 v100, v87
	v_add_f32_e32 v99, v235, v97
	v_pk_add_f32 v[80:81], v[98:99], v[82:83]
	v_exp_f32_e32 v83, v102
	v_pk_add_f32 v[84:85], v[80:81], v[80:81] op_sel_hi:[0,1]
	v_exp_f32_e32 v99, v86
	v_exp_f32_e32 v84, v103
	v_exp_f32_e32 v102, v89
	v_cvt_pk_bf16_f32 v82, v97, v82
	v_add_f32_e32 v101, v99, v83
	v_pk_add_f32 v[80:81], v[100:101], v[84:85]
	v_exp_f32_e32 v85, v104
	v_pk_add_f32 v[86:87], v[80:81], v[80:81] op_sel_hi:[0,1]
	v_exp_f32_e32 v101, v88
	v_exp_f32_e32 v86, v105
	v_exp_f32_e32 v104, v91
	v_cvt_pk_bf16_f32 v83, v83, v84
	v_add_f32_e32 v103, v101, v85
	v_pk_add_f32 v[80:81], v[102:103], v[86:87]
	v_exp_f32_e32 v87, v106
	v_pk_add_f32 v[88:89], v[80:81], v[80:81] op_sel_hi:[0,1]
	v_exp_f32_e32 v103, v90
	v_exp_f32_e32 v88, v107
	v_exp_f32_e32 v106, v93
	v_cvt_pk_bf16_f32 v84, v85, v86
	v_add_f32_e32 v105, v103, v87
	v_pk_add_f32 v[80:81], v[104:105], v[88:89]
	v_exp_f32_e32 v89, v108
	v_pk_add_f32 v[90:91], v[80:81], v[80:81] op_sel_hi:[0,1]
	v_exp_f32_e32 v105, v92
	v_exp_f32_e32 v90, v109
	v_exp_f32_e32 v108, v95
	v_cvt_pk_bf16_f32 v85, v87, v88
	v_add_f32_e32 v107, v105, v89
	v_pk_add_f32 v[80:81], v[106:107], v[90:91]
	v_exp_f32_e32 v91, v110
	v_pk_add_f32 v[92:93], v[80:81], v[80:81] op_sel_hi:[0,1]
	v_exp_f32_e32 v107, v94
	v_exp_f32_e32 v92, v111
	v_cvt_pk_bf16_f32 v86, v89, v90
	v_cvt_pk_bf16_f32 v88, v236, v14
	v_add_f32_e32 v109, v107, v91
	v_pk_add_f32 v[80:81], v[108:109], v[92:93]
	v_cvt_pk_bf16_f32 v87, v91, v92
	v_add_f32_e32 v80, v80, v81
	v_cvt_pk_bf16_f32 v81, v15, v96
	v_cvt_pk_bf16_f32 v89, v237, v234
	v_cvt_pk_bf16_f32 v90, v235, v98
	v_cvt_pk_bf16_f32 v91, v99, v100
	v_cvt_pk_bf16_f32 v92, v101, v102
	v_cvt_pk_bf16_f32 v93, v103, v104
	v_cvt_pk_bf16_f32 v94, v105, v106
	v_cvt_pk_bf16_f32 v95, v107, v108
	ds_read_b64_tr_b16 v[96:97], v226 offset:55424
	ds_read_b64_tr_b16 v[98:99], v226 offset:57984
	ds_read_b64_tr_b16 v[100:101], v226 offset:60544
	ds_read_b64_tr_b16 v[102:103], v226 offset:63104
	ds_read_b64_tr_b16 v[104:105], v227 offset:30848
	ds_read_b64_tr_b16 v[106:107], v227 offset:33408
	ds_read_b64_tr_b16 v[108:109], v227 offset:35968
	ds_read_b64_tr_b16 v[110:111], v227 offset:38528
	ds_read_b64_tr_b16 v[234:235], v226 offset:55488
	ds_read_b64_tr_b16 v[236:237], v226 offset:58048
	ds_read_b64_tr_b16 v[238:239], v226 offset:60608
	ds_read_b64_tr_b16 v[240:241], v226 offset:63168
	ds_read_b64_tr_b16 v[242:243], v227 offset:30912
	ds_read_b64_tr_b16 v[244:245], v227 offset:33472
	ds_read_b64_tr_b16 v[246:247], v227 offset:36032
	ds_read_b64_tr_b16 v[248:249], v227 offset:38592
	v_add_f32_e32 v203, v203, v80
	v_cvt_pk_bf16_f32 v80, v199, v0
	s_nop 1
	v_mfma_f32_32x32x16_bf16 v[64:79], v[152:155], v[80:83], v[64:79]
	s_waitcnt lgkmcnt(14)
	v_mfma_f32_32x32x16_bf16 v[48:63], v[164:167], v[80:83], v[48:63]
	v_mfma_f32_32x32x16_bf16 v[32:47], v[96:99], v[80:83], v[32:47]
	s_waitcnt lgkmcnt(6)
	v_mfma_f32_32x32x16_bf16 v[16:31], v[234:237], v[80:83], v[16:31]
	v_mfma_f32_32x32x16_bf16 v[64:79], v[160:163], v[84:87], v[64:79]
	v_mfma_f32_32x32x16_bf16 v[48:63], v[168:171], v[84:87], v[48:63]
	v_mfma_f32_32x32x16_bf16 v[32:47], v[100:103], v[84:87], v[32:47]
	s_waitcnt lgkmcnt(4)
	v_mfma_f32_32x32x16_bf16 v[16:31], v[238:241], v[84:87], v[16:31]
	v_mfma_f32_32x32x16_bf16 v[64:79], v[172:175], v[88:91], v[64:79]
	v_mfma_f32_32x32x16_bf16 v[48:63], v[176:179], v[88:91], v[48:63]
	v_mfma_f32_32x32x16_bf16 v[32:47], v[104:107], v[88:91], v[32:47]
	s_waitcnt lgkmcnt(2)
	v_mfma_f32_32x32x16_bf16 v[16:31], v[242:245], v[88:91], v[16:31]
	v_mfma_f32_32x32x16_bf16 v[64:79], v[156:159], v[92:95], v[64:79]
	v_mfma_f32_32x32x16_bf16 v[48:63], v[148:151], v[92:95], v[48:63]
	v_mfma_f32_32x32x16_bf16 v[32:47], v[108:111], v[92:95], v[32:47]
	s_waitcnt lgkmcnt(0)
	v_mfma_f32_32x32x16_bf16 v[16:31], v[246:249], v[92:95], v[16:31]
	s_cmp_ge_u32 s37, s39
	s_cselect_b64 s[10:11], -1, 0
	s_branch .LBB0_42

.Lah_skip0:
	global_load_dwordx4 v[6:9], v[206:207], off offset:16
	global_load_dwordx4 v[144:147], v[206:207], off
	global_load_dwordx4 v[2:5], v[206:207], off offset:1552
	global_load_dwordx4 v[10:13], v[206:207], off offset:1536
	s_add_i32 s10, s37, 3
	s_min_i32 s10, s10, s40
	s_mul_i32 s76, s10, 0x50000
	v_lshl_add_u64 v[14:15], v[204:205], 0, s[76:77]
	s_branch .LBB0_49
.Lah_skip1:
	global_load_dwordx4 v[136:139], v[14:15], off offset:16
	global_load_dwordx4 v[128:131], v[14:15], off
	global_load_dwordx4 v[140:143], v[14:15], off offset:1552
	global_load_dwordx4 v[132:135], v[14:15], off offset:1536
	s_add_i32 s10, s37, 4
	s_min_i32 s10, s10, s40
	s_mul_i32 s76, s10, 0x50000
	v_lshl_add_u64 v[206:207], v[204:205], 0, s[76:77]
	s_branch .LBB0_55
